# rows phase: loop-invariant ds_bpermute lane indices computed once before the row loop; 150 per-step index instructions removed by liveness-checked DCE
# speedup vs baseline: 1.0139x; 1.0139x over previous
.LBB0_449:
	v_and_b32_e32 v39, 32, v34
	v_cmp_eq_u32_e64 s[40:41], 0, v39
	v_and_b32_e32 v39, 16, v34
	v_lshrrev_b32_e32 v42, 1, v35
	v_readlane_b32 s2, v251, 14
	v_cmp_eq_u32_e64 s[42:43], 0, v39
	v_cmp_eq_u32_e64 s[46:47], 0, v38
	v_and_b32_e32 v38, 16, v42
	v_mov_b32_e32 v39, v9
	v_readlane_b32 s3, v251, 15
	s_add_i32 s1, 0, 0x1c000
	v_add_u32_e32 v101, s1, v8
	v_lshl_add_u64 v[38:39], s[2:3], 0, v[38:39]
	v_readlane_b32 s1, v253, 26
	v_readlane_b32 s2, v251, 59
	v_mov_b32_e32 v37, v9
	s_mul_i32 s4, s36, 24
	v_add_u32_e32 v102, s1, v8
	v_readlane_b32 s3, v251, 60
	s_ashr_i32 s1, s0, 31
	s_lshl_b32 s58, s36, 4
	s_lshl_b32 s59, s36, 5
	v_lshl_add_u64 v[66:67], s[2:3], 0, v[36:37]
	s_ashr_i32 s5, s4, 31
	s_lshl_b64 s[2:3], s[0:1], 5
	v_and_b32_e32 v40, 8, v34
	s_add_u32 s2, s2, 0x1e500000
	v_cmp_eq_u32_e64 s[44:45], 0, v40
	v_and_b32_e32 v40, 8, v42
	v_mov_b32_e32 v41, v9
	s_addc_u32 s3, s3, 0
	v_lshrrev_b32_e32 v34, 1, v34
	v_lshl_add_u64 v[38:39], v[38:39], 0, v[40:41]
	v_and_b32_e32 v42, 4, v42
	v_mov_b32_e32 v43, v9
	v_and_or_b32 v34, v34, 16, s2
	v_mov_b32_e32 v69, s3
	s_lshl_b64 s[2:3], s[0:1], 11
	v_lshl_add_u64 v[62:63], s[70:71], 0, v[36:37]
	v_add_u32_e32 v100, 0, v8
	v_lshl_add_u64 v[64:65], v[38:39], 0, v[42:43]
	v_or3_b32 v68, v34, v40, v42
	s_lshl_b64 s[6:7], s[4:5], 5
	v_lshl_or_b32 v70, v35, 3, s2
	v_mov_b32_e32 v71, s3
	s_lshl_b64 s[34:35], s[4:5], 11
	s_mov_b64 s[50:51], s[0:1]
	v_xor_b32_e32 v244, 1, v220
	v_xor_b32_e32 v245, 2, v220
	v_xor_b32_e32 v246, 4, v220
	v_xor_b32_e32 v247, 8, v220
	v_xor_b32_e32 v248, 16, v220
	v_xor_b32_e32 v249, 32, v220
	v_lshlrev_b32_e32 v244, 2, v244
	v_lshlrev_b32_e32 v245, 2, v245
	v_lshlrev_b32_e32 v246, 2, v246
	v_lshlrev_b32_e32 v247, 2, v247
	v_lshlrev_b32_e32 v248, 2, v248
	v_lshlrev_b32_e32 v249, 2, v249
	s_branch .LBB0_452

.LBB0_463:
	s_waitcnt vmcnt(11)
	v_and_b32_e32 v121, 0xffff0000, v52
	s_waitcnt vmcnt(10)
	v_and_b32_e32 v125, 0xffff0000, v50
	v_lshlrev_b32_e32 v120, 16, v52
	v_lshlrev_b32_e32 v124, 16, v50
	v_mov_b32_e32 v86, v121
	v_mov_b32_e32 v87, v125
	v_lshlrev_b32_e32 v122, 16, v53
	v_lshlrev_b32_e32 v126, 16, v51
	v_mov_b32_e32 v84, v120
	v_mov_b32_e32 v85, v124
	v_pk_mul_f32 v[86:87], v[86:87], v[86:87]
	v_and_b32_e32 v123, 0xffff0000, v53
	v_and_b32_e32 v127, 0xffff0000, v51
	v_pk_fma_f32 v[84:85], v[84:85], v[84:85], v[86:87]
	v_mov_b32_e32 v86, v122
	v_mov_b32_e32 v87, v126
	v_mov_b32_e32 v88, v123
	v_mov_b32_e32 v89, v127
	v_pk_fma_f32 v[84:85], v[86:87], v[86:87], v[84:85]
	s_waitcnt vmcnt(9)
	v_and_b32_e32 v129, 0xffff0000, v56
	s_waitcnt vmcnt(8)
	v_and_b32_e32 v133, 0xffff0000, v54
	v_pk_fma_f32 v[84:85], v[88:89], v[88:89], v[84:85]
	v_lshlrev_b32_e32 v128, 16, v56
	v_lshlrev_b32_e32 v132, 16, v54
	v_mov_b32_e32 v88, v133
	v_mov_b32_e32 v89, v129
	v_lshlrev_b32_e32 v130, 16, v57
	v_lshlrev_b32_e32 v134, 16, v55
	v_mov_b32_e32 v86, v132
	v_mov_b32_e32 v87, v128
	v_pk_mul_f32 v[88:89], v[88:89], v[88:89]
	v_and_b32_e32 v131, 0xffff0000, v57
	v_and_b32_e32 v135, 0xffff0000, v55
	v_pk_fma_f32 v[86:87], v[86:87], v[86:87], v[88:89]
	v_mov_b32_e32 v88, v134
	v_mov_b32_e32 v89, v130
	v_mov_b32_e32 v90, v135
	v_mov_b32_e32 v91, v131
	v_pk_fma_f32 v[86:87], v[88:89], v[88:89], v[86:87]
	v_add_f32_e32 v84, v84, v85
	v_pk_fma_f32 v[86:87], v[90:91], v[90:91], v[86:87]
	v_add_f32_e32 v84, v87, v84
	v_add_f32_e32 v84, v86, v84
	ds_bpermute_b32 v85, v249, v84
	s_add_i32 s2, s50, 0xffff8000
	s_waitcnt lgkmcnt(0)
	v_add_f32_e32 v84, v84, v85
	ds_bpermute_b32 v85, v248, v84
	v_readlane_b32 s60, v251, 10
	s_cmpk_gt_i32 s50, 0x7fff
	s_waitcnt lgkmcnt(0)
	v_add_f32_e32 v84, v84, v85
	ds_bpermute_b32 v85, v247, v84
	v_readlane_b32 s61, v251, 11
	v_readlane_b32 s18, v252, 8
	s_waitcnt lgkmcnt(0)
	v_add_f32_e32 v84, v84, v85
	ds_bpermute_b32 v85, v246, v84
	s_cselect_b32 s3, 0, s51
	s_cselect_b32 s2, s2, s50
	s_waitcnt lgkmcnt(0)
	v_add_f32_e32 v84, v84, v85
	ds_bpermute_b32 v85, v245, v84
	s_cselect_b32 s19, s18, s61
	v_readlane_b32 s18, v252, 7
	s_waitcnt lgkmcnt(0)
	v_add_f32_e32 v104, v84, v85
	ds_bpermute_b32 v105, v244, v104
	s_cselect_b32 s18, s18, s60
	s_lshl_b64 s[2:3], s[2:3], 12
	s_add_u32 s18, s18, s2
	s_addc_u32 s19, s19, s3
	s_and_b32 s2, s1, 0xfffff000
	s_waitcnt lgkmcnt(0)
	v_add_f32_e32 v104, v104, v105
	v_add_u32_e32 v103, s2, v100
	v_fmamk_f32 v104, v104, 0x3a800000, v218
	s_mov_b32 s2, 0x800000
	v_mul_f32_e32 v105, 0x4b800000, v104
	v_cmp_gt_f32_e32 vcc, s2, v104
	ds_read_b128 v[84:87], v100 offset:32768
	ds_read_b128 v[88:91], v100 offset:33792
	ds_read_b128 v[92:95], v103 offset:40960
	ds_read_b128 v[96:99], v103 offset:41984
	v_cndmask_b32_e32 v104, v104, v105, vcc
	v_rsq_f32_e32 v136, v104
	ds_read_b128 v[104:107], v100 offset:34816
	ds_read_b128 v[108:111], v100 offset:35840
	ds_read_b128 v[112:115], v103 offset:43008
	ds_read_b128 v[116:119], v103 offset:44032
	v_readlane_b32 s62, v251, 12
	v_readlane_b32 s63, v251, 13
	v_mul_f32_e32 v103, 0x45800000, v136
	v_cndmask_b32_e32 v136, v136, v103, vcc
	v_pk_mul_f32 v[120:121], v[136:137], v[120:121] op_sel_hi:[0,1]
	s_waitcnt lgkmcnt(7)
	v_pk_mul_f32 v[84:85], v[84:85], v[120:121]
	s_waitcnt lgkmcnt(5)
	v_pk_fma_f32 v[0:1], v[92:93], v[84:85], v[0:1]
	v_pk_mul_f32 v[84:85], v[136:137], v[122:123] op_sel_hi:[0,1]
	v_pk_mul_f32 v[84:85], v[86:87], v[84:85]
	s_nop 0
	v_pk_fma_f32 v[2:3], v[94:95], v[84:85], v[2:3]
	v_pk_mul_f32 v[84:85], v[136:137], v[124:125] op_sel_hi:[0,1]
	v_pk_mul_f32 v[84:85], v[88:89], v[84:85]
	global_store_dwordx4 v8, v[0:3], s[18:19] nt
	s_waitcnt lgkmcnt(4)
	v_pk_fma_f32 v[4:5], v[96:97], v[84:85], v[4:5]
	v_pk_mul_f32 v[84:85], v[136:137], v[126:127] op_sel_hi:[0,1]
	v_pk_mul_f32 v[84:85], v[90:91], v[84:85]
	s_nop 0
	v_pk_fma_f32 v[6:7], v[98:99], v[84:85], v[6:7]
	v_pk_mul_f32 v[84:85], v[136:137], v[128:129] op_sel_hi:[0,1]
	s_waitcnt lgkmcnt(3)
	v_pk_mul_f32 v[84:85], v[104:105], v[84:85]
	global_store_dwordx4 v8, v[4:7], s[18:19] offset:1024 nt
	s_waitcnt lgkmcnt(1)
	v_pk_fma_f32 v[10:11], v[112:113], v[84:85], v[10:11]
	v_pk_mul_f32 v[84:85], v[136:137], v[130:131] op_sel_hi:[0,1]
	v_pk_mul_f32 v[84:85], v[106:107], v[84:85]
	s_nop 0
	v_pk_fma_f32 v[12:13], v[114:115], v[84:85], v[12:13]
	v_pk_mul_f32 v[84:85], v[136:137], v[132:133] op_sel_hi:[0,1]
	v_pk_mul_f32 v[84:85], v[84:85], v[108:109]
	global_store_dwordx4 v8, v[10:13], s[18:19] offset:2048 nt
	s_waitcnt lgkmcnt(0)
	v_pk_fma_f32 v[14:15], v[116:117], v[84:85], v[14:15]
	v_pk_mul_f32 v[84:85], v[136:137], v[134:135] op_sel_hi:[0,1]
	v_pk_mul_f32 v[84:85], v[84:85], v[110:111]
	s_nop 0
	v_pk_fma_f32 v[16:17], v[118:119], v[84:85], v[16:17]
	global_store_dwordx4 v8, v[14:17], s[18:19] offset:3072 nt
.LBB0_464:
	v_readlane_b32 s2, v254, 27
	v_readlane_b32 s3, v254, 28
	s_andn2_b64 vcc, exec, s[2:3]
	s_nop 0
	v_cndmask_b32_e64 v84, 0, 1, s[2:3]
	v_cmp_ne_u32_e64 s[48:49], 1, v84
	s_cbranch_vccnz .LBB0_468
	s_waitcnt vmcnt(10)
	v_mov_b32_e32 v86, v5
	v_mov_b32_e32 v87, v1
	v_mov_b32_e32 v84, v4
	v_mov_b32_e32 v85, v0
	v_pk_mul_f32 v[86:87], v[86:87], v[86:87]
	s_waitcnt vmcnt(8)
	v_mov_b32_e32 v88, v15
	v_pk_fma_f32 v[84:85], v[84:85], v[84:85], v[86:87]
	v_mov_b32_e32 v86, v6
	v_mov_b32_e32 v87, v2
	v_pk_fma_f32 v[84:85], v[86:87], v[86:87], v[84:85]
	v_mov_b32_e32 v86, v7
	v_mov_b32_e32 v87, v3
	v_mov_b32_e32 v89, v11
	v_pk_fma_f32 v[84:85], v[86:87], v[86:87], v[84:85]
	v_mov_b32_e32 v86, v14
	v_mov_b32_e32 v87, v10
	v_pk_mul_f32 v[88:89], v[88:89], v[88:89]
	v_add_f32_e32 v84, v84, v85
	v_pk_fma_f32 v[86:87], v[86:87], v[86:87], v[88:89]
	v_mov_b32_e32 v88, v16
	v_mov_b32_e32 v89, v12
	v_pk_fma_f32 v[86:87], v[88:89], v[88:89], v[86:87]
	v_mov_b32_e32 v88, v17
	v_mov_b32_e32 v89, v13
	v_pk_fma_f32 v[86:87], v[88:89], v[88:89], v[86:87]
	v_add_f32_e32 v84, v87, v84
	v_add_f32_e32 v84, v86, v84
	s_mov_b32 s2, 0x800000
	s_and_b32 s1, s1, 0xfffff000
	ds_bpermute_b32 v86, v249, v84
	v_add_u32_e32 v98, s1, v101
	ds_read_b128 v[104:107], v98
	v_readlane_b32 s60, v251, 10
	v_readlane_b32 s62, v251, 12
	s_waitcnt lgkmcnt(1)
	v_add_f32_e32 v84, v84, v86
	v_readlane_b32 s63, v251, 13
	v_readlane_b32 s61, v251, 11
	ds_bpermute_b32 v86, v248, v84
	s_waitcnt lgkmcnt(0)
	v_add_f32_e32 v84, v84, v86
	s_nop 1
	ds_bpermute_b32 v86, v247, v84
	s_waitcnt lgkmcnt(0)
	v_add_f32_e32 v84, v84, v86
	s_nop 1
	ds_bpermute_b32 v86, v246, v84
	s_waitcnt lgkmcnt(0)
	v_add_f32_e32 v84, v84, v86
	s_nop 1
	ds_bpermute_b32 v86, v245, v84
	s_waitcnt lgkmcnt(0)
	v_add_f32_e32 v84, v84, v86
	s_nop 1
	ds_bpermute_b32 v85, v244, v84
	ds_read_b128 v[86:89], v100 offset:36864
	s_waitcnt lgkmcnt(1)
	v_add_f32_e32 v84, v84, v85
	v_fmamk_f32 v84, v84, 0x3a800000, v218
	v_cmp_gt_f32_e32 vcc, s2, v84
	v_mul_f32_e32 v85, 0x4b800000, v84
	s_nop 0
	v_cndmask_b32_e32 v84, v84, v85, vcc
	v_rsq_f32_e32 v84, v84
	s_nop 0
	v_mul_f32_e32 v85, 0x45800000, v84
	v_cndmask_b32_e32 v84, v84, v85, vcc
	v_add_u32_e32 v85, s1, v102
	ds_read_b128 v[108:111], v85
	v_pk_mul_f32 v[90:91], v[0:1], v[84:85] op_sel_hi:[1,0]
	s_mov_b32 s1, 0xb00000
	s_waitcnt lgkmcnt(1)
	v_pk_mul_f32 v[86:87], v[86:87], v[90:91]
	v_pk_add_f32 v[90:91], v[104:105], 1.0 op_sel_hi:[1,0]
	v_pk_mul_f32 v[118:119], v[4:5], v[84:85] op_sel_hi:[1,0]
	s_waitcnt lgkmcnt(0)
	v_pk_fma_f32 v[112:113], v[90:91], v[86:87], v[108:109]
	v_pk_mul_f32 v[86:87], v[2:3], v[84:85] op_sel_hi:[1,0]
	s_nop 0
	v_pk_mul_f32 v[86:87], v[88:89], v[86:87]
	v_pk_add_f32 v[88:89], v[106:107], 1.0 op_sel_hi:[1,0]
	s_nop 0
	v_pk_fma_f32 v[110:111], v[88:89], v[86:87], v[110:111]
	v_lshl_add_u64 v[86:87], s[62:63], 0, v[70:71]
	v_add_co_u32_e32 v86, vcc, s1, v86
	v_cvt_pk_bf16_f32 v88, v112, v113
	v_cvt_pk_bf16_f32 v89, v110, v111
	v_addc_co_u32_e32 v87, vcc, 0, v87, vcc
	global_store_dwordx2 v[86:87], v[88:89], off
	ds_read_b128 v[88:91], v100
	s_waitcnt lgkmcnt(0)
	v_mul_f32_e32 v89, v89, v113
	v_fmac_f32_e32 v89, v88, v112
	v_fmac_f32_e32 v89, v90, v110
	v_fmac_f32_e32 v89, v91, v111
	v_add_f32_e32 v107, 0, v89
	ds_read_b128 v[88:91], v100 offset:4096
	s_waitcnt lgkmcnt(0)
	v_mul_f32_e32 v89, v89, v113
	v_fmac_f32_e32 v89, v88, v112
	v_fmac_f32_e32 v89, v90, v110
	v_fmac_f32_e32 v89, v91, v111
	v_add_f32_e32 v109, 0, v89
	ds_read_b128 v[88:91], v100 offset:8192
	s_waitcnt lgkmcnt(0)
	v_mul_f32_e32 v89, v89, v113
	v_fmac_f32_e32 v89, v88, v112
	v_fmac_f32_e32 v89, v90, v110
	v_fmac_f32_e32 v89, v91, v111
	v_add_f32_e32 v108, 0, v89
	ds_read_b128 v[88:91], v100 offset:12288
	s_waitcnt lgkmcnt(0)
	v_mul_f32_e32 v89, v89, v113
	v_fmac_f32_e32 v89, v88, v112
	v_fmac_f32_e32 v89, v90, v110
	v_fmac_f32_e32 v89, v91, v111
	v_add_f32_e32 v106, 0, v89
	ds_read_b128 v[88:91], v100 offset:16384
	s_waitcnt lgkmcnt(0)
	v_mul_f32_e32 v89, v89, v113
	v_fmac_f32_e32 v89, v88, v112
	v_fmac_f32_e32 v89, v90, v110
	v_fmac_f32_e32 v89, v91, v111
	v_add_f32_e32 v105, 0, v89
	ds_read_b128 v[88:91], v100 offset:20480
	s_waitcnt lgkmcnt(0)
	v_mul_f32_e32 v89, v89, v113
	v_fmac_f32_e32 v89, v88, v112
	v_fmac_f32_e32 v89, v90, v110
	v_fmac_f32_e32 v89, v91, v111
	v_add_f32_e32 v104, 0, v89
	ds_read_b128 v[88:91], v100 offset:24576
	s_waitcnt lgkmcnt(0)
	v_mul_f32_e32 v89, v89, v113
	v_fmac_f32_e32 v89, v88, v112
	v_fmac_f32_e32 v89, v90, v110
	v_fmac_f32_e32 v89, v91, v111
	v_add_f32_e32 v103, 0, v89
	ds_read_b128 v[88:91], v100 offset:28672
	s_waitcnt lgkmcnt(0)
	v_mul_f32_e32 v89, v113, v89
	v_fmac_f32_e32 v89, v112, v88
	v_fmac_f32_e32 v89, v110, v90
	v_fmac_f32_e32 v89, v111, v91
	v_add_f32_e32 v99, 0, v89
	ds_read_b128 v[88:91], v100 offset:37888
	ds_read_b128 v[110:113], v98 offset:1024
	ds_read_b128 v[114:117], v85 offset:1024
	s_waitcnt lgkmcnt(2)
	v_pk_mul_f32 v[88:89], v[118:119], v[88:89]
	s_waitcnt lgkmcnt(1)
	v_pk_add_f32 v[110:111], v[110:111], 1.0 op_sel_hi:[1,0]
	s_waitcnt lgkmcnt(0)
	v_pk_fma_f32 v[88:89], v[88:89], v[110:111], v[114:115]
	v_pk_mul_f32 v[110:111], v[6:7], v[84:85] op_sel_hi:[1,0]
	s_nop 0
	v_pk_mul_f32 v[90:91], v[110:111], v[90:91]
	v_pk_add_f32 v[110:111], v[112:113], 1.0 op_sel_hi:[1,0]
	s_nop 0
	v_pk_fma_f32 v[90:91], v[90:91], v[110:111], v[116:117]
	v_cvt_pk_bf16_f32 v110, v88, v89
	v_cvt_pk_bf16_f32 v111, v90, v91
	global_store_dwordx2 v[86:87], v[110:111], off offset:512
	ds_read_b128 v[110:113], v100 offset:1024
	s_waitcnt lgkmcnt(0)
	v_mul_f32_e32 v111, v89, v111
	v_fmac_f32_e32 v111, v88, v110
	v_fmac_f32_e32 v111, v90, v112
	v_fmac_f32_e32 v111, v91, v113
	v_add_f32_e32 v107, v107, v111
	ds_read_b128 v[110:113], v100 offset:5120
	s_waitcnt lgkmcnt(0)
	v_mul_f32_e32 v111, v89, v111
	v_fmac_f32_e32 v111, v88, v110
	v_fmac_f32_e32 v111, v90, v112
	v_fmac_f32_e32 v111, v91, v113
	v_add_f32_e32 v116, v109, v111
	ds_read_b128 v[110:113], v100 offset:9216
	s_waitcnt lgkmcnt(0)
	v_mul_f32_e32 v109, v89, v111
	v_fmac_f32_e32 v109, v88, v110
	v_fmac_f32_e32 v109, v90, v112
	v_fmac_f32_e32 v109, v91, v113
	v_add_f32_e32 v117, v108, v109
	ds_read_b128 v[108:111], v100 offset:13312
	s_waitcnt lgkmcnt(0)
	v_mul_f32_e32 v109, v89, v109
	v_fmac_f32_e32 v109, v88, v108
	v_fmac_f32_e32 v109, v90, v110
	v_fmac_f32_e32 v109, v91, v111
	v_add_f32_e32 v106, v106, v109
	ds_read_b128 v[108:111], v100 offset:17408
	s_waitcnt lgkmcnt(0)
	v_mul_f32_e32 v109, v89, v109
	v_fmac_f32_e32 v109, v88, v108
	v_fmac_f32_e32 v109, v90, v110
	v_fmac_f32_e32 v109, v91, v111
	v_add_f32_e32 v118, v105, v109
	ds_read_b128 v[108:111], v100 offset:21504
	s_waitcnt lgkmcnt(0)
	v_mul_f32_e32 v105, v89, v109
	v_fmac_f32_e32 v105, v88, v108
	v_fmac_f32_e32 v105, v90, v110
	v_fmac_f32_e32 v105, v91, v111
	ds_read_b128 v[108:111], v100 offset:25600
	v_add_f32_e32 v119, v104, v105
	s_waitcnt lgkmcnt(0)
	v_mul_f32_e32 v104, v89, v109
	v_fmac_f32_e32 v104, v88, v108
	v_fmac_f32_e32 v104, v90, v110
	v_fmac_f32_e32 v104, v91, v111
	ds_read_b128 v[108:111], v100 offset:29696
	v_add_f32_e32 v120, v103, v104
	v_pk_mul_f32 v[104:105], v[10:11], v[84:85] op_sel_hi:[1,0]
	s_waitcnt lgkmcnt(0)
	v_mul_f32_e32 v89, v89, v109
	v_fmac_f32_e32 v89, v88, v108
	v_fmac_f32_e32 v89, v90, v110
	v_fmac_f32_e32 v89, v91, v111
	v_add_f32_e32 v121, v99, v89
	ds_read_b128 v[88:91], v100 offset:38912
	ds_read_b128 v[108:111], v98 offset:2048
	ds_read_b128 v[112:115], v85 offset:2048
	s_waitcnt lgkmcnt(2)
	v_pk_mul_f32 v[88:89], v[104:105], v[88:89]
	s_waitcnt lgkmcnt(1)
	v_pk_add_f32 v[104:105], v[108:109], 1.0 op_sel_hi:[1,0]
	s_waitcnt lgkmcnt(0)
	v_pk_fma_f32 v[112:113], v[88:89], v[104:105], v[112:113]
	v_pk_mul_f32 v[88:89], v[12:13], v[84:85] op_sel_hi:[1,0]
	s_nop 0
	v_pk_mul_f32 v[88:89], v[88:89], v[90:91]
	v_pk_add_f32 v[90:91], v[110:111], 1.0 op_sel_hi:[1,0]
	s_nop 0
	v_pk_fma_f32 v[110:111], v[88:89], v[90:91], v[114:115]
	v_cvt_pk_bf16_f32 v88, v112, v113
	v_cvt_pk_bf16_f32 v89, v110, v111
	global_store_dwordx2 v[86:87], v[88:89], off offset:1024
	ds_read_b128 v[88:91], v100 offset:2048
	s_waitcnt lgkmcnt(0)
	v_mul_f32_e32 v89, v113, v89
	v_fmac_f32_e32 v89, v112, v88
	v_fmac_f32_e32 v89, v110, v90
	v_fmac_f32_e32 v89, v111, v91
	v_add_f32_e32 v105, v107, v89
	ds_read_b128 v[88:91], v100 offset:6144
	s_waitcnt lgkmcnt(0)
	v_mul_f32_e32 v89, v113, v89
	v_fmac_f32_e32 v89, v112, v88
	v_fmac_f32_e32 v89, v110, v90
	v_fmac_f32_e32 v89, v111, v91
	v_add_f32_e32 v122, v116, v89
	ds_read_b128 v[88:91], v100 offset:10240
	s_waitcnt lgkmcnt(0)
	v_mul_f32_e32 v89, v113, v89
	v_fmac_f32_e32 v89, v112, v88
	v_fmac_f32_e32 v89, v110, v90
	v_fmac_f32_e32 v89, v111, v91
	v_add_f32_e32 v123, v117, v89
	ds_read_b128 v[88:91], v100 offset:14336
	s_waitcnt lgkmcnt(0)
	v_mul_f32_e32 v89, v113, v89
	v_fmac_f32_e32 v89, v112, v88
	v_fmac_f32_e32 v89, v110, v90
	v_fmac_f32_e32 v89, v111, v91
	v_add_f32_e32 v104, v106, v89
	ds_read_b128 v[88:91], v100 offset:18432
	ds_read_b128 v[106:109], v100 offset:30720
	s_waitcnt lgkmcnt(1)
	v_mul_f32_e32 v89, v113, v89
	v_fmac_f32_e32 v89, v112, v88
	v_fmac_f32_e32 v89, v110, v90
	v_fmac_f32_e32 v89, v111, v91
	v_add_f32_e32 v103, v118, v89
	ds_read_b128 v[88:91], v100 offset:22528
	s_waitcnt lgkmcnt(0)
	v_mul_f32_e32 v89, v113, v89
	v_fmac_f32_e32 v89, v112, v88
	v_fmac_f32_e32 v89, v110, v90
	v_fmac_f32_e32 v89, v111, v91
	v_add_f32_e32 v99, v119, v89
	ds_read_b128 v[88:91], v100 offset:26624
	s_waitcnt lgkmcnt(0)
	v_mul_f32_e32 v89, v113, v89
	v_fmac_f32_e32 v89, v112, v88
	v_mul_f32_e32 v88, v113, v107
	v_fmac_f32_e32 v88, v112, v106
	v_fmac_f32_e32 v89, v110, v90
	v_fmac_f32_e32 v88, v110, v108
	v_fmac_f32_e32 v89, v111, v91
	v_fmac_f32_e32 v88, v111, v109
	ds_read_b128 v[106:109], v100 offset:39936
	ds_read_b128 v[110:113], v98 offset:3072
	ds_read_b128 v[114:117], v85 offset:3072
	v_add_f32_e32 v91, v120, v89
	v_add_f32_e32 v90, v121, v88
	v_pk_mul_f32 v[88:89], v[14:15], v[84:85] op_sel_hi:[1,0]
	v_pk_mul_f32 v[84:85], v[16:17], v[84:85] op_sel_hi:[1,0]
	s_waitcnt lgkmcnt(2)
	v_pk_mul_f32 v[88:89], v[88:89], v[106:107]
	s_waitcnt lgkmcnt(1)
	v_pk_add_f32 v[106:107], v[110:111], 1.0 op_sel_hi:[1,0]
	v_pk_mul_f32 v[84:85], v[84:85], v[108:109]
	s_waitcnt lgkmcnt(0)
	v_pk_fma_f32 v[88:89], v[88:89], v[106:107], v[114:115]
	v_pk_add_f32 v[106:107], v[112:113], 1.0 op_sel_hi:[1,0]
	s_nop 0
	v_pk_fma_f32 v[84:85], v[84:85], v[106:107], v[116:117]
	v_cvt_pk_bf16_f32 v106, v88, v89
	v_cvt_pk_bf16_f32 v107, v84, v85
	global_store_dwordx2 v[86:87], v[106:107], off offset:1536
	ds_read_b128 v[106:109], v100 offset:3072
	s_waitcnt lgkmcnt(0)
	v_mul_f32_e32 v86, v89, v107
	v_fmac_f32_e32 v86, v88, v106
	v_fmac_f32_e32 v86, v84, v108
	v_fmac_f32_e32 v86, v85, v109
	ds_read_b128 v[106:109], v100 offset:7168
	v_add_f32_e32 v86, v105, v86
	s_waitcnt lgkmcnt(0)
	v_mul_f32_e32 v87, v89, v107
	v_fmac_f32_e32 v87, v88, v106
	v_fmac_f32_e32 v87, v84, v108
	v_fmac_f32_e32 v87, v85, v109
	ds_read_b128 v[106:109], v100 offset:11264
	v_add_f32_e32 v87, v122, v87
	s_waitcnt lgkmcnt(0)
	v_mul_f32_e32 v98, v89, v107
	v_fmac_f32_e32 v98, v88, v106
	v_fmac_f32_e32 v98, v84, v108
	v_fmac_f32_e32 v98, v85, v109
	ds_read_b128 v[106:109], v100 offset:15360
	v_add_f32_e32 v98, v123, v98
	s_waitcnt lgkmcnt(0)
	v_mul_f32_e32 v105, v89, v107
	v_fmac_f32_e32 v105, v88, v106
	v_fmac_f32_e32 v105, v84, v108
	v_fmac_f32_e32 v105, v85, v109
	v_add_f32_e32 v108, v104, v105
	ds_read_b128 v[104:107], v100 offset:19456
	s_waitcnt lgkmcnt(0)
	v_mul_f32_e32 v105, v89, v105
	v_fmac_f32_e32 v105, v88, v104
	v_fmac_f32_e32 v105, v84, v106
	v_fmac_f32_e32 v105, v85, v107
	v_add_f32_e32 v103, v103, v105
	ds_read_b128 v[104:107], v100 offset:23552
	s_waitcnt lgkmcnt(0)
	v_mul_f32_e32 v105, v89, v105
	v_fmac_f32_e32 v105, v88, v104
	v_fmac_f32_e32 v105, v84, v106
	v_fmac_f32_e32 v105, v85, v107
	v_add_f32_e32 v99, v99, v105
	ds_read_b128 v[104:107], v100 offset:27648
	s_waitcnt lgkmcnt(0)
	v_mul_f32_e32 v105, v89, v105
	v_fmac_f32_e32 v105, v88, v104
	v_fmac_f32_e32 v105, v84, v106
	v_fmac_f32_e32 v105, v85, v107
	v_add_f32_e32 v91, v91, v105
	ds_read_b128 v[104:107], v100 offset:31744
	s_waitcnt lgkmcnt(0)
	v_mul_f32_e32 v89, v89, v105
	v_fmac_f32_e32 v89, v88, v104
	v_fmac_f32_e32 v89, v84, v106
	v_fmac_f32_e32 v89, v85, v107
	v_cndmask_b32_e64 v85, v103, v86, s[40:41]
	v_cndmask_b32_e64 v86, v86, v103, s[40:41]
	ds_bpermute_b32 v86, v249, v86
	v_cndmask_b32_e64 v88, v98, v91, s[40:41]
	ds_bpermute_b32 v88, v249, v88
	v_add_f32_e32 v84, v90, v89
	s_waitcnt lgkmcnt(1)
	v_add_f32_e32 v85, v85, v86
	v_cndmask_b32_e64 v86, v99, v87, s[40:41]
	v_cndmask_b32_e64 v87, v87, v99, s[40:41]
	ds_bpermute_b32 v87, v249, v87
	s_waitcnt lgkmcnt(0)
	v_add_f32_e32 v86, v86, v87
	v_cndmask_b32_e64 v87, v91, v98, s[40:41]
	v_add_f32_e32 v87, v87, v88
	v_cndmask_b32_e64 v88, v84, v108, s[40:41]
	v_cndmask_b32_e64 v84, v108, v84, s[40:41]
	ds_bpermute_b32 v84, v249, v84
	s_waitcnt lgkmcnt(0)
	v_add_f32_e32 v84, v88, v84
	v_cndmask_b32_e64 v88, v87, v85, s[42:43]
	v_cndmask_b32_e64 v85, v85, v87, s[42:43]
	v_cndmask_b32_e64 v87, v84, v86, s[42:43]
	v_cndmask_b32_e64 v84, v86, v84, s[42:43]
	ds_bpermute_b32 v85, v248, v85
	ds_bpermute_b32 v84, v248, v84
	s_waitcnt lgkmcnt(1)
	v_add_f32_e32 v85, v88, v85
	s_waitcnt lgkmcnt(0)
	v_add_f32_e32 v84, v87, v84
	v_cndmask_b32_e64 v86, v84, v85, s[44:45]
	v_cndmask_b32_e64 v84, v85, v84, s[44:45]
	ds_bpermute_b32 v84, v247, v84
	s_waitcnt lgkmcnt(0)
	v_add_f32_e32 v84, v86, v84
	ds_bpermute_b32 v85, v246, v84
	s_waitcnt lgkmcnt(0)
	v_add_f32_e32 v84, v84, v85
	ds_bpermute_b32 v85, v245, v84
	s_waitcnt lgkmcnt(0)
	v_add_f32_e32 v84, v84, v85
	ds_bpermute_b32 v85, v244, v84
	s_and_saveexec_b64 s[18:19], s[46:47]
	s_cbranch_execz .LBB0_467
	v_readlane_b32 s60, v251, 10
	v_readlane_b32 s62, v251, 12
	v_readlane_b32 s63, v251, 13
	s_waitcnt lgkmcnt(0)
	v_add_f32_e32 v86, v84, v85
	v_readlane_b32 s61, v251, 11
	v_lshl_add_u64 v[84:85], s[62:63], 0, v[68:69]
	global_store_dword v[84:85], v86, off

.LBB0_486:
	s_waitcnt vmcnt(11)
	v_and_b32_e32 v121, 0xffff0000, v60
	s_waitcnt vmcnt(10)
	v_and_b32_e32 v125, 0xffff0000, v58
	v_lshlrev_b32_e32 v120, 16, v60
	v_lshlrev_b32_e32 v124, 16, v58
	v_mov_b32_e32 v86, v121
	v_mov_b32_e32 v87, v125
	v_lshlrev_b32_e32 v122, 16, v61
	v_lshlrev_b32_e32 v126, 16, v59
	v_mov_b32_e32 v84, v120
	v_mov_b32_e32 v85, v124
	v_pk_mul_f32 v[86:87], v[86:87], v[86:87]
	v_and_b32_e32 v123, 0xffff0000, v61
	v_and_b32_e32 v127, 0xffff0000, v59
	v_pk_fma_f32 v[84:85], v[84:85], v[84:85], v[86:87]
	v_mov_b32_e32 v86, v122
	v_mov_b32_e32 v87, v126
	v_mov_b32_e32 v88, v123
	v_mov_b32_e32 v89, v127
	v_pk_fma_f32 v[84:85], v[86:87], v[86:87], v[84:85]
	s_waitcnt vmcnt(9)
	v_and_b32_e32 v129, 0xffff0000, v74
	s_waitcnt vmcnt(8)
	v_and_b32_e32 v133, 0xffff0000, v72
	v_pk_fma_f32 v[84:85], v[88:89], v[88:89], v[84:85]
	v_lshlrev_b32_e32 v128, 16, v74
	v_lshlrev_b32_e32 v132, 16, v72
	v_mov_b32_e32 v88, v133
	v_mov_b32_e32 v89, v129
	v_lshlrev_b32_e32 v130, 16, v75
	v_lshlrev_b32_e32 v134, 16, v73
	v_mov_b32_e32 v86, v132
	v_mov_b32_e32 v87, v128
	v_pk_mul_f32 v[88:89], v[88:89], v[88:89]
	v_and_b32_e32 v131, 0xffff0000, v75
	v_and_b32_e32 v135, 0xffff0000, v73
	v_pk_fma_f32 v[86:87], v[86:87], v[86:87], v[88:89]
	v_mov_b32_e32 v88, v134
	v_mov_b32_e32 v89, v130
	v_mov_b32_e32 v90, v135
	v_mov_b32_e32 v91, v131
	v_pk_fma_f32 v[86:87], v[88:89], v[88:89], v[86:87]
	v_add_f32_e32 v84, v84, v85
	v_pk_fma_f32 v[86:87], v[90:91], v[90:91], v[86:87]
	v_add_f32_e32 v84, v87, v84
	v_add_f32_e32 v84, v86, v84
	ds_bpermute_b32 v85, v249, v84
	s_add_i32 s2, s56, 0xffff8000
	s_waitcnt lgkmcnt(0)
	v_add_f32_e32 v84, v84, v85
	ds_bpermute_b32 v85, v248, v84
	s_ashr_i32 s3, s56, 31
	v_readlane_b32 s60, v251, 10
	s_waitcnt lgkmcnt(0)
	v_add_f32_e32 v84, v84, v85
	ds_bpermute_b32 v85, v247, v84
	s_cmpk_gt_i32 s56, 0x7fff
	v_readlane_b32 s61, v251, 11
	s_waitcnt lgkmcnt(0)
	v_add_f32_e32 v84, v84, v85
	ds_bpermute_b32 v85, v246, v84
	v_readlane_b32 s18, v252, 8
	s_cselect_b32 s3, 0, s3
	s_waitcnt lgkmcnt(0)
	v_add_f32_e32 v84, v84, v85
	ds_bpermute_b32 v85, v245, v84
	s_cselect_b32 s2, s2, s56
	s_cselect_b32 s19, s18, s61
	s_waitcnt lgkmcnt(0)
	v_add_f32_e32 v104, v84, v85
	ds_bpermute_b32 v105, v244, v104
	v_readlane_b32 s18, v252, 7
	s_cselect_b32 s18, s18, s60
	s_lshl_b64 s[2:3], s[2:3], 12
	s_add_u32 s18, s18, s2
	s_addc_u32 s19, s19, s3
	s_and_b32 s2, s1, 0xfffff000
	s_waitcnt lgkmcnt(0)
	v_add_f32_e32 v104, v104, v105
	v_add_u32_e32 v103, s2, v100
	v_fmamk_f32 v104, v104, 0x3a800000, v218
	s_mov_b32 s2, 0x800000
	v_mul_f32_e32 v105, 0x4b800000, v104
	v_cmp_gt_f32_e32 vcc, s2, v104
	ds_read_b128 v[84:87], v100 offset:32768
	ds_read_b128 v[88:91], v100 offset:33792
	ds_read_b128 v[92:95], v103 offset:40960
	ds_read_b128 v[96:99], v103 offset:41984
	v_cndmask_b32_e32 v104, v104, v105, vcc
	v_rsq_f32_e32 v136, v104
	ds_read_b128 v[104:107], v100 offset:34816
	ds_read_b128 v[108:111], v100 offset:35840
	ds_read_b128 v[112:115], v103 offset:43008
	ds_read_b128 v[116:119], v103 offset:44032
	v_readlane_b32 s62, v251, 12
	v_readlane_b32 s63, v251, 13
	v_mul_f32_e32 v103, 0x45800000, v136
	v_cndmask_b32_e32 v136, v136, v103, vcc
	v_pk_mul_f32 v[120:121], v[136:137], v[120:121] op_sel_hi:[0,1]
	s_waitcnt lgkmcnt(7)
	v_pk_mul_f32 v[84:85], v[84:85], v[120:121]
	s_waitcnt lgkmcnt(5)
	v_pk_fma_f32 v[18:19], v[92:93], v[84:85], v[18:19]
	v_pk_mul_f32 v[84:85], v[136:137], v[122:123] op_sel_hi:[0,1]
	v_pk_mul_f32 v[84:85], v[86:87], v[84:85]
	s_nop 0
	v_pk_fma_f32 v[20:21], v[94:95], v[84:85], v[20:21]
	v_pk_mul_f32 v[84:85], v[136:137], v[124:125] op_sel_hi:[0,1]
	v_pk_mul_f32 v[84:85], v[88:89], v[84:85]
	global_store_dwordx4 v8, v[18:21], s[18:19] nt
	s_waitcnt lgkmcnt(4)
	v_pk_fma_f32 v[22:23], v[96:97], v[84:85], v[22:23]
	v_pk_mul_f32 v[84:85], v[136:137], v[126:127] op_sel_hi:[0,1]
	v_pk_mul_f32 v[84:85], v[90:91], v[84:85]
	s_nop 0
	v_pk_fma_f32 v[24:25], v[98:99], v[84:85], v[24:25]
	v_pk_mul_f32 v[84:85], v[136:137], v[128:129] op_sel_hi:[0,1]
	s_waitcnt lgkmcnt(3)
	v_pk_mul_f32 v[84:85], v[104:105], v[84:85]
	global_store_dwordx4 v8, v[22:25], s[18:19] offset:1024 nt
	s_waitcnt lgkmcnt(1)
	v_pk_fma_f32 v[26:27], v[112:113], v[84:85], v[26:27]
	v_pk_mul_f32 v[84:85], v[136:137], v[130:131] op_sel_hi:[0,1]
	v_pk_mul_f32 v[84:85], v[106:107], v[84:85]
	s_nop 0
	v_pk_fma_f32 v[28:29], v[114:115], v[84:85], v[28:29]
	v_pk_mul_f32 v[84:85], v[136:137], v[132:133] op_sel_hi:[0,1]
	v_pk_mul_f32 v[84:85], v[84:85], v[108:109]
	global_store_dwordx4 v8, v[26:29], s[18:19] offset:2048 nt
	s_waitcnt lgkmcnt(0)
	v_pk_fma_f32 v[30:31], v[116:117], v[84:85], v[30:31]
	v_pk_mul_f32 v[84:85], v[136:137], v[134:135] op_sel_hi:[0,1]
	v_pk_mul_f32 v[84:85], v[84:85], v[110:111]
	s_nop 0
	v_pk_fma_f32 v[32:33], v[118:119], v[84:85], v[32:33]
	global_store_dwordx4 v8, v[30:33], s[18:19] offset:3072 nt
	s_and_b64 vcc, exec, s[48:49]
	s_cbranch_vccnz .LBB0_481
.LBB0_487:
	s_waitcnt vmcnt(10)
	v_mov_b32_e32 v86, v23
	v_mov_b32_e32 v87, v19
	v_mov_b32_e32 v84, v22
	v_mov_b32_e32 v85, v18
	v_pk_mul_f32 v[86:87], v[86:87], v[86:87]
	s_waitcnt vmcnt(8)
	v_mov_b32_e32 v88, v31
	v_pk_fma_f32 v[84:85], v[84:85], v[84:85], v[86:87]
	v_mov_b32_e32 v86, v24
	v_mov_b32_e32 v87, v20
	v_pk_fma_f32 v[84:85], v[86:87], v[86:87], v[84:85]
	v_mov_b32_e32 v86, v25
	v_mov_b32_e32 v87, v21
	v_mov_b32_e32 v89, v27
	v_pk_fma_f32 v[84:85], v[86:87], v[86:87], v[84:85]
	v_mov_b32_e32 v86, v30
	v_mov_b32_e32 v87, v26
	v_pk_mul_f32 v[88:89], v[88:89], v[88:89]
	v_add_f32_e32 v84, v84, v85
	v_pk_fma_f32 v[86:87], v[86:87], v[86:87], v[88:89]
	v_mov_b32_e32 v88, v32
	v_mov_b32_e32 v89, v28
	v_pk_fma_f32 v[86:87], v[88:89], v[88:89], v[86:87]
	v_mov_b32_e32 v88, v33
	v_mov_b32_e32 v89, v29
	v_pk_fma_f32 v[86:87], v[88:89], v[88:89], v[86:87]
	v_add_f32_e32 v84, v87, v84
	v_add_f32_e32 v84, v86, v84
	s_mov_b32 s2, 0x800000
	s_and_b32 s1, s1, 0xfffff000
	ds_bpermute_b32 v86, v249, v84
	v_add_u32_e32 v98, s1, v101
	ds_read_b128 v[94:97], v98
	v_add_u32_e32 v93, s1, v102
	ds_read_b128 v[110:113], v93
	s_waitcnt lgkmcnt(2)
	v_add_f32_e32 v84, v84, v86
	s_ashr_i32 s57, s56, 31
	ds_read_b128 v[114:117], v100
	ds_bpermute_b32 v86, v248, v84
	s_waitcnt lgkmcnt(0)
	v_add_f32_e32 v84, v84, v86
	s_nop 1
	ds_bpermute_b32 v86, v247, v84
	s_waitcnt lgkmcnt(0)
	v_add_f32_e32 v84, v84, v86
	s_nop 1
	ds_bpermute_b32 v86, v246, v84
	s_waitcnt lgkmcnt(0)
	v_add_f32_e32 v84, v84, v86
	s_nop 1
	ds_bpermute_b32 v86, v245, v84
	s_waitcnt lgkmcnt(0)
	v_add_f32_e32 v84, v84, v86
	s_nop 1
	ds_bpermute_b32 v85, v244, v84
	ds_read_b128 v[86:89], v100 offset:36864
	s_waitcnt lgkmcnt(1)
	v_add_f32_e32 v84, v84, v85
	v_fmamk_f32 v84, v84, 0x3a800000, v218
	v_cmp_gt_f32_e32 vcc, s2, v84
	v_mul_f32_e32 v85, 0x4b800000, v84
	s_lshl_b64 s[2:3], s[56:57], 11
	v_cndmask_b32_e32 v84, v84, v85, vcc
	v_rsq_f32_e32 v84, v84
	s_nop 0
	v_mul_f32_e32 v85, 0x45800000, v84
	v_cndmask_b32_e32 v92, v84, v85, vcc
	v_pk_mul_f32 v[84:85], v[18:19], v[92:93] op_sel_hi:[1,0]
	v_pk_mul_f32 v[118:119], v[22:23], v[92:93] op_sel_hi:[1,0]
	s_waitcnt lgkmcnt(0)
	v_pk_mul_f32 v[84:85], v[86:87], v[84:85]
	v_pk_add_f32 v[86:87], v[94:95], 1.0 op_sel_hi:[1,0]
	s_nop 0
	v_pk_fma_f32 v[86:87], v[86:87], v[84:85], v[110:111]
	v_pk_mul_f32 v[84:85], v[20:21], v[92:93] op_sel_hi:[1,0]
	v_mul_f32_e32 v94, v115, v87
	v_pk_mul_f32 v[84:85], v[88:89], v[84:85]
	v_pk_add_f32 v[88:89], v[96:97], 1.0 op_sel_hi:[1,0]
	v_fmac_f32_e32 v94, v114, v86
	v_pk_fma_f32 v[84:85], v[88:89], v[84:85], v[112:113]
	ds_read_b128 v[88:91], v100 offset:4096
	v_fmac_f32_e32 v94, v116, v84
	v_fmac_f32_e32 v94, v117, v85
	v_add_f32_e32 v109, 0, v94
	ds_read_b128 v[94:97], v100 offset:8192
	s_waitcnt lgkmcnt(1)
	v_mul_f32_e32 v89, v89, v87
	v_fmac_f32_e32 v89, v88, v86
	v_fmac_f32_e32 v89, v90, v84
	v_fmac_f32_e32 v89, v91, v85
	v_add_f32_e32 v122, 0, v89
	ds_read_b128 v[88:91], v100 offset:12288
	s_waitcnt lgkmcnt(1)
	v_mul_f32_e32 v95, v95, v87
	v_fmac_f32_e32 v95, v94, v86
	v_fmac_f32_e32 v95, v96, v84
	v_fmac_f32_e32 v95, v97, v85
	v_add_f32_e32 v123, 0, v95
	ds_read_b128 v[94:97], v100 offset:16384
	s_waitcnt lgkmcnt(1)
	v_mul_f32_e32 v89, v89, v87
	v_fmac_f32_e32 v89, v88, v86
	v_fmac_f32_e32 v89, v90, v84
	v_fmac_f32_e32 v89, v91, v85
	v_add_f32_e32 v99, 0, v89
	ds_read_b128 v[88:91], v100 offset:20480
	ds_read_b128 v[110:113], v100 offset:24576
	s_waitcnt lgkmcnt(2)
	v_mul_f32_e32 v95, v95, v87
	v_fmac_f32_e32 v95, v94, v86
	v_fmac_f32_e32 v95, v96, v84
	s_waitcnt lgkmcnt(1)
	v_mul_f32_e32 v89, v89, v87
	v_fmac_f32_e32 v89, v88, v86
	v_fmac_f32_e32 v89, v90, v84
	v_fmac_f32_e32 v95, v97, v85
	v_fmac_f32_e32 v89, v91, v85
	v_add_f32_e32 v96, 0, v95
	v_add_f32_e32 v95, 0, v89
	ds_read_b128 v[88:91], v100 offset:28672
	s_waitcnt lgkmcnt(1)
	v_mul_f32_e32 v94, v111, v87
	v_fmac_f32_e32 v94, v110, v86
	v_fmac_f32_e32 v94, v112, v84
	v_fmac_f32_e32 v94, v113, v85
	s_waitcnt lgkmcnt(0)
	v_mul_f32_e32 v97, v87, v89
	v_fmac_f32_e32 v97, v86, v88
	v_fmac_f32_e32 v97, v84, v90
	v_fmac_f32_e32 v97, v85, v91
	ds_read_b128 v[88:91], v100 offset:37888
	ds_read_b128 v[110:113], v98 offset:1024
	ds_read_b128 v[114:117], v93 offset:1024
	v_add_f32_e32 v94, 0, v94
	v_add_f32_e32 v97, 0, v97
	s_waitcnt lgkmcnt(2)
	v_pk_mul_f32 v[88:89], v[118:119], v[88:89]
	ds_read_b128 v[118:121], v100 offset:1024
	s_waitcnt lgkmcnt(2)
	v_pk_add_f32 v[110:111], v[110:111], 1.0 op_sel_hi:[1,0]
	v_cvt_pk_bf16_f32 v86, v86, v87
	s_waitcnt lgkmcnt(1)
	v_pk_fma_f32 v[88:89], v[88:89], v[110:111], v[114:115]
	v_pk_mul_f32 v[110:111], v[24:25], v[92:93] op_sel_hi:[1,0]
	s_nop 0
	v_pk_mul_f32 v[90:91], v[110:111], v[90:91]
	v_pk_add_f32 v[110:111], v[112:113], 1.0 op_sel_hi:[1,0]
	s_nop 0
	v_pk_fma_f32 v[90:91], v[90:91], v[110:111], v[116:117]
	ds_read_b128 v[110:113], v100 offset:5120
	s_waitcnt lgkmcnt(1)
	v_mul_f32_e32 v114, v89, v119
	v_fmac_f32_e32 v114, v88, v118
	v_fmac_f32_e32 v114, v90, v120
	v_fmac_f32_e32 v114, v91, v121
	v_add_f32_e32 v109, v109, v114
	ds_read_b128 v[114:117], v100 offset:9216
	s_waitcnt lgkmcnt(1)
	v_mul_f32_e32 v111, v89, v111
	v_fmac_f32_e32 v111, v88, v110
	v_fmac_f32_e32 v111, v90, v112
	v_fmac_f32_e32 v111, v91, v113
	v_add_f32_e32 v126, v122, v111
	ds_read_b128 v[110:113], v100 offset:13312
	s_waitcnt lgkmcnt(1)
	v_mul_f32_e32 v115, v89, v115
	v_fmac_f32_e32 v115, v88, v114
	v_fmac_f32_e32 v115, v90, v116
	v_fmac_f32_e32 v115, v91, v117
	v_add_f32_e32 v127, v123, v115
	ds_read_b128 v[114:117], v100 offset:17408
	s_waitcnt lgkmcnt(1)
	v_mul_f32_e32 v111, v89, v111
	v_fmac_f32_e32 v111, v88, v110
	v_fmac_f32_e32 v111, v90, v112
	v_fmac_f32_e32 v111, v91, v113
	v_add_f32_e32 v99, v99, v111
	ds_read_b128 v[110:113], v100 offset:21504
	s_waitcnt lgkmcnt(1)
	v_mul_f32_e32 v115, v89, v115
	v_fmac_f32_e32 v115, v88, v114
	v_fmac_f32_e32 v115, v90, v116
	v_fmac_f32_e32 v115, v91, v117
	v_add_f32_e32 v128, v96, v115
	ds_read_b128 v[114:117], v100 offset:25600
	s_waitcnt lgkmcnt(1)
	v_mul_f32_e32 v96, v89, v111
	v_fmac_f32_e32 v96, v88, v110
	v_fmac_f32_e32 v96, v90, v112
	v_fmac_f32_e32 v96, v91, v113
	ds_read_b128 v[110:113], v100 offset:29696
	v_add_f32_e32 v129, v95, v96
	s_waitcnt lgkmcnt(1)
	v_mul_f32_e32 v95, v89, v115
	v_fmac_f32_e32 v95, v88, v114
	v_fmac_f32_e32 v95, v90, v116
	v_fmac_f32_e32 v95, v91, v117
	v_add_f32_e32 v130, v94, v95
	s_waitcnt lgkmcnt(0)
	v_mul_f32_e32 v94, v89, v111
	v_fmac_f32_e32 v94, v88, v110
	v_fmac_f32_e32 v94, v90, v112
	v_fmac_f32_e32 v94, v91, v113
	ds_read_b128 v[110:113], v100 offset:38912
	ds_read_b128 v[114:117], v98 offset:2048
	ds_read_b128 v[118:121], v93 offset:2048
	ds_read_b128 v[122:125], v100 offset:2048
	v_add_f32_e32 v131, v97, v94
	v_pk_mul_f32 v[94:95], v[26:27], v[92:93] op_sel_hi:[1,0]
	s_waitcnt lgkmcnt(2)
	v_pk_add_f32 v[96:97], v[114:115], 1.0 op_sel_hi:[1,0]
	v_pk_mul_f32 v[94:95], v[94:95], v[110:111]
	v_pk_add_f32 v[110:111], v[116:117], 1.0 op_sel_hi:[1,0]
	s_waitcnt lgkmcnt(1)
	v_pk_fma_f32 v[94:95], v[94:95], v[96:97], v[118:119]
	v_pk_mul_f32 v[96:97], v[28:29], v[92:93] op_sel_hi:[1,0]
	s_nop 0
	v_pk_mul_f32 v[96:97], v[96:97], v[112:113]
	s_nop 0
	v_pk_fma_f32 v[96:97], v[96:97], v[110:111], v[120:121]
	ds_read_b128 v[110:113], v100 offset:6144
	s_waitcnt lgkmcnt(1)
	v_mul_f32_e32 v114, v95, v123
	v_fmac_f32_e32 v114, v94, v122
	v_fmac_f32_e32 v114, v96, v124
	v_fmac_f32_e32 v114, v97, v125
	v_add_f32_e32 v132, v109, v114
	ds_read_b128 v[114:117], v100 offset:10240
	s_waitcnt lgkmcnt(1)
	v_mul_f32_e32 v109, v95, v111
	v_fmac_f32_e32 v109, v94, v110
	v_fmac_f32_e32 v109, v96, v112
	v_fmac_f32_e32 v109, v97, v113
	ds_read_b128 v[110:113], v100 offset:14336
	v_add_f32_e32 v133, v126, v109
	s_waitcnt lgkmcnt(1)
	v_mul_f32_e32 v109, v95, v115
	v_fmac_f32_e32 v109, v94, v114
	v_fmac_f32_e32 v109, v96, v116
	v_fmac_f32_e32 v109, v97, v117
	ds_read_b128 v[114:117], v100 offset:18432
	ds_read_b128 v[118:121], v100 offset:22528
	v_add_f32_e32 v134, v127, v109
	s_waitcnt lgkmcnt(2)
	v_mul_f32_e32 v109, v95, v111
	v_fmac_f32_e32 v109, v94, v110
	v_fmac_f32_e32 v109, v96, v112
	v_fmac_f32_e32 v109, v97, v113
	v_add_f32_e32 v113, v99, v109
	s_waitcnt lgkmcnt(1)
	v_mul_f32_e32 v99, v95, v115
	v_fmac_f32_e32 v99, v94, v114
	v_fmac_f32_e32 v99, v96, v116
	v_fmac_f32_e32 v99, v97, v117
	ds_read_b128 v[114:117], v100 offset:26624
	v_add_f32_e32 v111, v128, v99
	s_waitcnt lgkmcnt(1)
	v_mul_f32_e32 v99, v95, v119
	v_fmac_f32_e32 v99, v94, v118
	v_fmac_f32_e32 v99, v96, v120
	v_fmac_f32_e32 v99, v97, v121
	ds_read_b128 v[118:121], v100 offset:30720
	v_add_f32_e32 v110, v129, v99
	s_waitcnt lgkmcnt(1)
	v_mul_f32_e32 v99, v95, v115
	v_fmac_f32_e32 v99, v94, v114
	v_fmac_f32_e32 v99, v96, v116
	v_fmac_f32_e32 v99, v97, v117
	v_add_f32_e32 v109, v130, v99
	s_waitcnt lgkmcnt(0)
	v_mul_f32_e32 v99, v95, v119
	v_fmac_f32_e32 v99, v94, v118
	v_fmac_f32_e32 v99, v96, v120
	v_fmac_f32_e32 v99, v97, v121
	ds_read_b128 v[114:117], v100 offset:39936
	ds_read_b128 v[118:121], v98 offset:3072
	ds_read_b128 v[122:125], v93 offset:3072
	v_add_f32_e32 v112, v131, v99
	v_pk_mul_f32 v[98:99], v[30:31], v[92:93] op_sel_hi:[1,0]
	v_pk_mul_f32 v[92:93], v[32:33], v[92:93] op_sel_hi:[1,0]
	s_waitcnt lgkmcnt(2)
	v_pk_mul_f32 v[98:99], v[98:99], v[114:115]
	s_waitcnt lgkmcnt(1)
	v_pk_add_f32 v[114:115], v[118:119], 1.0 op_sel_hi:[1,0]
	v_pk_mul_f32 v[92:93], v[92:93], v[116:117]
	s_waitcnt lgkmcnt(0)
	v_pk_fma_f32 v[98:99], v[98:99], v[114:115], v[122:123]
	v_pk_add_f32 v[114:115], v[120:121], 1.0 op_sel_hi:[1,0]
	ds_read_b128 v[126:129], v100 offset:3072
	v_pk_fma_f32 v[92:93], v[92:93], v[114:115], v[124:125]
	ds_read_b128 v[114:117], v100 offset:7168
	s_waitcnt lgkmcnt(1)
	v_mul_f32_e32 v118, v99, v127
	v_fmac_f32_e32 v118, v98, v126
	s_waitcnt lgkmcnt(0)
	v_mul_f32_e32 v115, v99, v115
	v_fmac_f32_e32 v115, v98, v114
	v_fmac_f32_e32 v118, v92, v128
	v_fmac_f32_e32 v115, v92, v116
	v_fmac_f32_e32 v118, v93, v129
	v_fmac_f32_e32 v115, v93, v117
	v_add_f32_e32 v122, v132, v118
	ds_read_b128 v[118:121], v100 offset:11264
	v_add_f32_e32 v123, v133, v115
	ds_read_b128 v[114:117], v100 offset:15360
	s_waitcnt lgkmcnt(1)
	v_mul_f32_e32 v119, v99, v119
	v_fmac_f32_e32 v119, v98, v118
	s_waitcnt lgkmcnt(0)
	v_mul_f32_e32 v115, v99, v115
	v_fmac_f32_e32 v115, v98, v114
	v_fmac_f32_e32 v119, v92, v120
	v_fmac_f32_e32 v115, v92, v116
	v_fmac_f32_e32 v119, v93, v121
	v_fmac_f32_e32 v115, v93, v117
	v_add_f32_e32 v124, v134, v119
	ds_read_b128 v[118:121], v100 offset:19456
	v_add_f32_e32 v113, v113, v115
	ds_read_b128 v[114:117], v100 offset:23552
	s_waitcnt lgkmcnt(1)
	v_mul_f32_e32 v119, v99, v119
	v_fmac_f32_e32 v119, v98, v118
	s_waitcnt lgkmcnt(0)
	v_mul_f32_e32 v115, v99, v115
	v_fmac_f32_e32 v115, v98, v114
	v_fmac_f32_e32 v119, v92, v120
	v_fmac_f32_e32 v115, v92, v116
	v_fmac_f32_e32 v119, v93, v121
	v_fmac_f32_e32 v115, v93, v117
	v_add_f32_e32 v111, v111, v119
	ds_read_b128 v[118:121], v100 offset:27648
	v_add_f32_e32 v110, v110, v115
	ds_read_b128 v[114:117], v100 offset:31744
	s_waitcnt lgkmcnt(1)
	v_mul_f32_e32 v119, v99, v119
	v_fmac_f32_e32 v119, v98, v118
	s_waitcnt lgkmcnt(0)
	v_mul_f32_e32 v115, v99, v115
	v_fmac_f32_e32 v115, v98, v114
	v_cndmask_b32_e64 v114, v122, v111, s[40:41]
	ds_bpermute_b32 v114, v249, v114
	v_fmac_f32_e32 v119, v92, v120
	v_fmac_f32_e32 v115, v92, v116
	v_fmac_f32_e32 v119, v93, v121
	v_fmac_f32_e32 v115, v93, v117
	v_add_f32_e32 v109, v109, v119
	v_add_f32_e32 v112, v112, v115
	v_cndmask_b32_e64 v111, v111, v122, s[40:41]
	s_waitcnt lgkmcnt(0)
	v_add_f32_e32 v111, v111, v114
	v_cndmask_b32_e64 v114, v110, v123, s[40:41]
	v_cndmask_b32_e64 v110, v123, v110, s[40:41]
	v_cndmask_b32_e64 v115, v124, v109, s[40:41]
	v_cndmask_b32_e64 v116, v113, v112, s[40:41]
	ds_bpermute_b32 v110, v249, v110
	ds_bpermute_b32 v115, v249, v115
	ds_bpermute_b32 v108, v249, v116
	v_cndmask_b32_e64 v109, v109, v124, s[40:41]
	v_cndmask_b32_e64 v112, v112, v113, s[40:41]
	s_waitcnt lgkmcnt(2)
	v_add_f32_e32 v110, v114, v110
	s_waitcnt lgkmcnt(1)
	v_add_f32_e32 v109, v109, v115
	s_waitcnt lgkmcnt(0)
	v_add_f32_e32 v108, v112, v108
	v_cndmask_b32_e64 v112, v111, v109, s[42:43]
	v_cndmask_b32_e64 v113, v110, v108, s[42:43]
	ds_bpermute_b32 v112, v248, v112
	ds_bpermute_b32 v107, v248, v113
	v_cndmask_b32_e64 v109, v109, v111, s[42:43]
	v_cndmask_b32_e64 v108, v108, v110, s[42:43]
	s_waitcnt lgkmcnt(1)
	v_add_f32_e32 v109, v109, v112
	s_waitcnt lgkmcnt(0)
	v_add_f32_e32 v107, v108, v107
	v_cndmask_b32_e64 v108, v109, v107, s[44:45]
	ds_bpermute_b32 v106, v247, v108
	v_cndmask_b32_e64 v87, v107, v109, s[44:45]
	s_waitcnt lgkmcnt(0)
	v_add_f32_e32 v108, v87, v106
	ds_bpermute_b32 v105, v246, v108
	v_cvt_pk_bf16_f32 v87, v84, v85
	v_cvt_pk_bf16_f32 v84, v88, v89
	v_lshl_add_u64 v[106:107], v[66:67], 0, s[2:3]
	v_cvt_pk_bf16_f32 v85, v90, v91
	s_waitcnt lgkmcnt(0)
	v_add_f32_e32 v88, v108, v105
	ds_bpermute_b32 v89, v245, v88
	global_store_dwordx2 v[106:107], v[84:85], off offset:512
	global_store_dwordx2 v[106:107], v[86:87], off
	v_cvt_pk_bf16_f32 v86, v94, v95
	v_cvt_pk_bf16_f32 v87, v96, v97
	s_waitcnt lgkmcnt(0)
	v_add_f32_e32 v84, v88, v89
	ds_bpermute_b32 v85, v244, v84
	global_store_dwordx2 v[106:107], v[86:87], off offset:1024
	v_cvt_pk_bf16_f32 v86, v98, v99
	v_cvt_pk_bf16_f32 v87, v92, v93
	global_store_dwordx2 v[106:107], v[86:87], off offset:1536
	s_and_saveexec_b64 s[18:19], s[46:47]
	s_cbranch_execz .LBB0_489
	s_lshl_b64 s[2:3], s[56:57], 5
	s_waitcnt lgkmcnt(0)
	v_add_f32_e32 v86, v84, v85
	v_lshl_add_u64 v[84:85], v[64:65], 0, s[2:3]
	global_store_dword v[84:85], v86, off

.LBB0_504:
	s_waitcnt vmcnt(6)
	v_lshlrev_b32_e32 v116, 16, v76
	v_and_b32_e32 v117, 0xffff0000, v76
	v_and_b32_e32 v113, 0xffff0000, v78
	v_lshlrev_b32_e32 v112, 16, v78
	v_lshlrev_b32_e32 v114, 16, v79
	v_and_b32_e32 v115, 0xffff0000, v79
	v_mov_b32_e32 v78, v113
	v_mov_b32_e32 v79, v117
	v_lshlrev_b32_e32 v118, 16, v77
	v_and_b32_e32 v119, 0xffff0000, v77
	v_mov_b32_e32 v76, v112
	v_mov_b32_e32 v77, v116
	v_pk_mul_f32 v[78:79], v[78:79], v[78:79]
	s_waitcnt vmcnt(5)
	v_and_b32_e32 v121, 0xffff0000, v82
	v_pk_fma_f32 v[76:77], v[76:77], v[76:77], v[78:79]
	v_mov_b32_e32 v78, v114
	v_mov_b32_e32 v79, v118
	s_waitcnt vmcnt(4)
	v_lshlrev_b32_e32 v124, 16, v80
	v_and_b32_e32 v125, 0xffff0000, v80
	v_lshlrev_b32_e32 v126, 16, v81
	v_and_b32_e32 v127, 0xffff0000, v81
	v_mov_b32_e32 v80, v115
	v_mov_b32_e32 v81, v119
	v_pk_fma_f32 v[76:77], v[78:79], v[78:79], v[76:77]
	v_lshlrev_b32_e32 v120, 16, v82
	v_pk_fma_f32 v[76:77], v[80:81], v[80:81], v[76:77]
	v_mov_b32_e32 v80, v121
	v_mov_b32_e32 v81, v125
	v_lshlrev_b32_e32 v122, 16, v83
	v_mov_b32_e32 v78, v120
	v_mov_b32_e32 v79, v124
	v_pk_mul_f32 v[80:81], v[80:81], v[80:81]
	v_and_b32_e32 v123, 0xffff0000, v83
	v_pk_fma_f32 v[78:79], v[78:79], v[78:79], v[80:81]
	v_mov_b32_e32 v80, v122
	v_mov_b32_e32 v81, v126
	v_mov_b32_e32 v82, v123
	v_mov_b32_e32 v83, v127
	v_pk_fma_f32 v[78:79], v[80:81], v[80:81], v[78:79]
	v_add_f32_e32 v76, v76, v77
	v_pk_fma_f32 v[78:79], v[82:83], v[82:83], v[78:79]
	v_add_f32_e32 v76, v76, v78
	v_add_f32_e32 v76, v76, v79
	ds_bpermute_b32 v77, v249, v76
	s_add_i32 s2, s52, 0xffff8000
	s_waitcnt lgkmcnt(0)
	v_add_f32_e32 v76, v76, v77
	ds_bpermute_b32 v77, v248, v76
	s_ashr_i32 s3, s52, 31
	v_readlane_b32 s60, v251, 10
	s_waitcnt lgkmcnt(0)
	v_add_f32_e32 v76, v76, v77
	ds_bpermute_b32 v77, v247, v76
	s_cmpk_gt_i32 s52, 0x7fff
	v_readlane_b32 s61, v251, 11
	s_waitcnt lgkmcnt(0)
	v_add_f32_e32 v76, v76, v77
	ds_bpermute_b32 v77, v246, v76
	v_readlane_b32 s18, v252, 8
	s_cselect_b32 s3, 0, s3
	s_waitcnt lgkmcnt(0)
	v_add_f32_e32 v76, v76, v77
	ds_bpermute_b32 v77, v245, v76
	s_cselect_b32 s2, s2, s52
	s_cselect_b32 s19, s18, s61
	s_waitcnt lgkmcnt(0)
	v_add_f32_e32 v92, v76, v77
	ds_bpermute_b32 v93, v244, v92
	v_readlane_b32 s18, v252, 7
	s_cselect_b32 s18, s18, s60
	s_lshl_b64 s[2:3], s[2:3], 12
	s_add_u32 s18, s18, s2
	s_addc_u32 s19, s19, s3
	s_and_b32 s2, s1, 0xfffff000
	s_waitcnt lgkmcnt(0)
	v_add_f32_e32 v92, v92, v93
	v_add_u32_e32 v103, s2, v100
	v_fmamk_f32 v92, v92, 0x3a800000, v218
	s_mov_b32 s2, 0x800000
	v_mul_f32_e32 v93, 0x4b800000, v92
	v_cmp_gt_f32_e32 vcc, s2, v92
	ds_read_b128 v[76:79], v100 offset:32768
	ds_read_b128 v[80:83], v100 offset:33792
	ds_read_b128 v[84:87], v103 offset:40960
	ds_read_b128 v[88:91], v103 offset:41984
	v_cndmask_b32_e32 v92, v92, v93, vcc
	v_rsq_f32_e32 v128, v92
	ds_read_b128 v[92:95], v100 offset:34816
	ds_read_b128 v[96:99], v100 offset:35840
	ds_read_b128 v[104:107], v103 offset:43008
	ds_read_b128 v[108:111], v103 offset:44032
	v_readlane_b32 s62, v251, 12
	v_readlane_b32 s63, v251, 13
	v_mul_f32_e32 v103, 0x45800000, v128
	v_cndmask_b32_e32 v128, v128, v103, vcc
	v_pk_mul_f32 v[112:113], v[128:129], v[112:113] op_sel_hi:[0,1]
	s_waitcnt lgkmcnt(7)
	v_pk_mul_f32 v[76:77], v[76:77], v[112:113]
	s_waitcnt lgkmcnt(5)
	v_pk_fma_f32 v[46:47], v[84:85], v[76:77], v[46:47]
	v_pk_mul_f32 v[76:77], v[128:129], v[114:115] op_sel_hi:[0,1]
	v_pk_mul_f32 v[76:77], v[78:79], v[76:77]
	s_nop 0
	v_pk_fma_f32 v[48:49], v[86:87], v[76:77], v[48:49]
	v_pk_mul_f32 v[76:77], v[128:129], v[116:117] op_sel_hi:[0,1]
	v_pk_mul_f32 v[76:77], v[80:81], v[76:77]
	global_store_dwordx4 v8, v[46:49], s[18:19] nt
	s_waitcnt lgkmcnt(4)
	v_pk_fma_f32 v[42:43], v[88:89], v[76:77], v[42:43]
	v_pk_mul_f32 v[76:77], v[128:129], v[118:119] op_sel_hi:[0,1]
	v_pk_mul_f32 v[76:77], v[82:83], v[76:77]
	s_nop 0
	v_pk_fma_f32 v[44:45], v[90:91], v[76:77], v[44:45]
	v_pk_mul_f32 v[76:77], v[128:129], v[120:121] op_sel_hi:[0,1]
	s_waitcnt lgkmcnt(3)
	v_pk_mul_f32 v[76:77], v[92:93], v[76:77]
	global_store_dwordx4 v8, v[42:45], s[18:19] offset:1024 nt
	s_waitcnt lgkmcnt(1)
	v_pk_fma_f32 v[38:39], v[104:105], v[76:77], v[38:39]
	v_pk_mul_f32 v[76:77], v[128:129], v[122:123] op_sel_hi:[0,1]
	v_pk_mul_f32 v[76:77], v[94:95], v[76:77]
	s_nop 0
	v_pk_fma_f32 v[40:41], v[106:107], v[76:77], v[40:41]
	v_pk_mul_f32 v[76:77], v[128:129], v[124:125] op_sel_hi:[0,1]
	v_pk_mul_f32 v[76:77], v[76:77], v[96:97]
	global_store_dwordx4 v8, v[38:41], s[18:19] offset:2048 nt
	s_waitcnt lgkmcnt(0)
	v_pk_fma_f32 v[34:35], v[108:109], v[76:77], v[34:35]
	v_pk_mul_f32 v[76:77], v[128:129], v[126:127] op_sel_hi:[0,1]
	v_pk_mul_f32 v[76:77], v[76:77], v[98:99]
	s_nop 0
	v_pk_fma_f32 v[36:37], v[110:111], v[76:77], v[36:37]
	global_store_dwordx4 v8, v[34:37], s[18:19] offset:3072 nt
	s_and_b64 vcc, exec, s[48:49]
	s_cbranch_vccnz .LBB0_451
.LBB0_505:
	s_waitcnt vmcnt(6)
	v_mov_b32_e32 v78, v43
	v_mov_b32_e32 v79, v47
	v_mov_b32_e32 v76, v42
	v_mov_b32_e32 v77, v46
	v_pk_mul_f32 v[78:79], v[78:79], v[78:79]
	s_waitcnt vmcnt(4)
	v_mov_b32_e32 v80, v35
	v_pk_fma_f32 v[76:77], v[76:77], v[76:77], v[78:79]
	v_mov_b32_e32 v78, v44
	v_mov_b32_e32 v79, v48
	v_pk_fma_f32 v[76:77], v[78:79], v[78:79], v[76:77]
	v_mov_b32_e32 v78, v45
	v_mov_b32_e32 v79, v49
	v_mov_b32_e32 v81, v39
	v_pk_fma_f32 v[76:77], v[78:79], v[78:79], v[76:77]
	v_mov_b32_e32 v78, v34
	v_mov_b32_e32 v79, v38
	v_pk_mul_f32 v[80:81], v[80:81], v[80:81]
	v_add_f32_e32 v76, v76, v77
	v_pk_fma_f32 v[78:79], v[78:79], v[78:79], v[80:81]
	v_mov_b32_e32 v80, v36
	v_mov_b32_e32 v81, v40
	v_pk_fma_f32 v[78:79], v[80:81], v[80:81], v[78:79]
	v_mov_b32_e32 v80, v37
	v_mov_b32_e32 v81, v41
	v_pk_fma_f32 v[78:79], v[80:81], v[80:81], v[78:79]
	v_and_b32_e32 v77, 64, v220
	v_add_f32_e32 v76, v79, v76
	v_add_f32_e32 v76, v78, v76
	v_add_u32_e32 v77, 64, v77
	s_mov_b32 s2, 0x800000
	s_and_b32 s1, s1, 0xfffff000
	ds_bpermute_b32 v78, v249, v76
	v_add_u32_e32 v84, s1, v101
	ds_read_b128 v[86:89], v100 offset:36864
	ds_read_b128 v[90:93], v84
	s_ashr_i32 s53, s52, 31
	s_waitcnt lgkmcnt(2)
	v_add_f32_e32 v76, v76, v78
	s_nop 1
	ds_bpermute_b32 v78, v248, v76
	s_waitcnt lgkmcnt(0)
	v_add_f32_e32 v76, v76, v78
	s_nop 1
	ds_bpermute_b32 v78, v247, v76
	s_waitcnt lgkmcnt(0)
	v_add_f32_e32 v76, v76, v78
	s_nop 1
	ds_bpermute_b32 v78, v246, v76
	s_waitcnt lgkmcnt(0)
	v_add_f32_e32 v76, v76, v78
	s_nop 1
	ds_bpermute_b32 v83, v245, v76
	s_waitcnt lgkmcnt(0)
	v_add_f32_e32 v76, v76, v83
	v_xor_b32_e32 v83, 1, v220
	v_cmp_lt_i32_e32 vcc, v83, v77
	s_nop 1
	v_cndmask_b32_e32 v77, v220, v83, vcc
	v_lshlrev_b32_e32 v77, 2, v77
	ds_bpermute_b32 v83, v244, v76
	s_waitcnt lgkmcnt(0)
	v_add_f32_e32 v76, v76, v83
	v_fmamk_f32 v76, v76, 0x3a800000, v218
	v_cmp_gt_f32_e32 vcc, s2, v76
	v_mul_f32_e32 v83, 0x4b800000, v76
	s_lshl_b64 s[2:3], s[52:53], 11
	v_cndmask_b32_e32 v76, v76, v83, vcc
	v_rsq_f32_e32 v76, v76
	s_nop 0
	v_mul_f32_e32 v83, 0x45800000, v76
	v_cndmask_b32_e32 v76, v76, v83, vcc
	v_add_u32_e32 v83, s1, v102
	ds_read_b128 v[94:97], v83
	v_pk_mul_f32 v[46:47], v[46:47], v[76:77] op_sel_hi:[1,0]
	v_pk_mul_f32 v[42:43], v[42:43], v[76:77] op_sel_hi:[1,0]
	v_pk_mul_f32 v[46:47], v[86:87], v[46:47]
	v_pk_add_f32 v[86:87], v[90:91], 1.0 op_sel_hi:[1,0]
	v_pk_mul_f32 v[44:45], v[44:45], v[76:77] op_sel_hi:[1,0]
	s_waitcnt lgkmcnt(0)
	v_pk_fma_f32 v[94:95], v[86:87], v[46:47], v[94:95]
	v_pk_mul_f32 v[46:47], v[48:49], v[76:77] op_sel_hi:[1,0]
	v_pk_add_f32 v[48:49], v[92:93], 1.0 op_sel_hi:[1,0]
	v_pk_mul_f32 v[46:47], v[88:89], v[46:47]
	ds_read_b128 v[86:89], v100
	v_pk_fma_f32 v[92:93], v[48:49], v[46:47], v[96:97]
	v_cvt_pk_bf16_f32 v48, v94, v95
	v_cvt_pk_bf16_f32 v49, v92, v93
	v_lshl_add_u64 v[46:47], v[66:67], 0, s[2:3]
	global_store_dwordx2 v[46:47], v[48:49], off
	s_waitcnt lgkmcnt(0)
	v_mul_f32_e32 v48, v87, v95
	v_fmac_f32_e32 v48, v86, v94
	v_fmac_f32_e32 v48, v88, v92
	v_fmac_f32_e32 v48, v89, v93
	ds_read_b128 v[86:89], v100 offset:4096
	v_add_f32_e32 v103, 0, v48
	v_pk_mul_f32 v[38:39], v[38:39], v[76:77] op_sel_hi:[1,0]
	v_pk_mul_f32 v[34:35], v[34:35], v[76:77] op_sel_hi:[1,0]
	v_pk_mul_f32 v[36:37], v[36:37], v[76:77] op_sel_hi:[1,0]
	s_waitcnt lgkmcnt(0)
	v_mul_f32_e32 v48, v87, v95
	v_fmac_f32_e32 v48, v86, v94
	v_fmac_f32_e32 v48, v88, v92
	v_fmac_f32_e32 v48, v89, v93
	ds_read_b128 v[86:89], v100 offset:8192
	v_add_f32_e32 v104, 0, v48
	s_waitcnt lgkmcnt(0)
	v_mul_f32_e32 v48, v87, v95
	v_fmac_f32_e32 v48, v86, v94
	v_fmac_f32_e32 v48, v88, v92
	v_fmac_f32_e32 v48, v89, v93
	ds_read_b128 v[86:89], v100 offset:12288
	v_add_f32_e32 v105, 0, v48
	s_waitcnt lgkmcnt(0)
	v_mul_f32_e32 v48, v87, v95
	v_fmac_f32_e32 v48, v86, v94
	v_fmac_f32_e32 v48, v88, v92
	v_fmac_f32_e32 v48, v89, v93
	ds_read_b128 v[88:91], v100 offset:16384
	v_add_f32_e32 v87, 0, v48
	s_waitcnt lgkmcnt(0)
	v_mul_f32_e32 v48, v89, v95
	v_fmac_f32_e32 v48, v88, v94
	v_fmac_f32_e32 v48, v90, v92
	v_fmac_f32_e32 v48, v91, v93
	ds_read_b128 v[88:91], v100 offset:20480
	v_add_f32_e32 v86, 0, v48
	s_waitcnt lgkmcnt(0)
	v_mul_f32_e32 v48, v89, v95
	v_fmac_f32_e32 v48, v88, v94
	v_fmac_f32_e32 v48, v90, v92
	v_fmac_f32_e32 v48, v91, v93
	ds_read_b128 v[88:91], v100 offset:24576
	v_add_f32_e32 v85, 0, v48
	s_waitcnt lgkmcnt(0)
	v_mul_f32_e32 v48, v89, v95
	v_fmac_f32_e32 v48, v88, v94
	v_fmac_f32_e32 v48, v90, v92
	v_fmac_f32_e32 v48, v91, v93
	ds_read_b128 v[88:91], v100 offset:28672
	v_add_f32_e32 v49, 0, v48
	s_waitcnt lgkmcnt(0)
	v_mul_f32_e32 v48, v95, v89
	v_fmac_f32_e32 v48, v94, v88
	v_fmac_f32_e32 v48, v92, v90
	v_fmac_f32_e32 v48, v93, v91
	ds_read_b128 v[88:91], v100 offset:37888
	ds_read_b128 v[92:95], v84 offset:1024
	ds_read_b128 v[96:99], v83 offset:1024
	v_add_f32_e32 v48, 0, v48
	s_waitcnt lgkmcnt(2)
	v_pk_mul_f32 v[42:43], v[42:43], v[88:89]
	s_waitcnt lgkmcnt(1)
	v_pk_add_f32 v[88:89], v[92:93], 1.0 op_sel_hi:[1,0]
	v_pk_mul_f32 v[44:45], v[44:45], v[90:91]
	s_waitcnt lgkmcnt(0)
	v_pk_fma_f32 v[42:43], v[42:43], v[88:89], v[96:97]
	v_pk_add_f32 v[88:89], v[94:95], 1.0 op_sel_hi:[1,0]
	s_nop 0
	v_pk_fma_f32 v[44:45], v[44:45], v[88:89], v[98:99]
	v_cvt_pk_bf16_f32 v88, v42, v43
	v_cvt_pk_bf16_f32 v89, v44, v45
	global_store_dwordx2 v[46:47], v[88:89], off offset:512
	ds_read_b128 v[88:91], v100 offset:1024
	s_waitcnt lgkmcnt(0)
	v_mul_f32_e32 v89, v43, v89
	v_fmac_f32_e32 v89, v42, v88
	v_fmac_f32_e32 v89, v44, v90
	v_fmac_f32_e32 v89, v45, v91
	ds_read_b128 v[90:93], v100 offset:5120
	v_add_f32_e32 v88, v103, v89
	s_waitcnt lgkmcnt(0)
	v_mul_f32_e32 v89, v43, v91
	v_fmac_f32_e32 v89, v42, v90
	v_fmac_f32_e32 v89, v44, v92
	v_fmac_f32_e32 v89, v45, v93
	ds_read_b128 v[90:93], v100 offset:9216
	v_add_f32_e32 v89, v104, v89
	s_waitcnt lgkmcnt(0)
	v_mul_f32_e32 v91, v43, v91
	v_fmac_f32_e32 v91, v42, v90
	v_fmac_f32_e32 v91, v44, v92
	v_fmac_f32_e32 v91, v45, v93
	v_add_f32_e32 v98, v105, v91
	ds_read_b128 v[90:93], v100 offset:13312
	s_waitcnt lgkmcnt(0)
	v_mul_f32_e32 v91, v43, v91
	v_fmac_f32_e32 v91, v42, v90
	v_fmac_f32_e32 v91, v44, v92
	v_fmac_f32_e32 v91, v45, v93
	v_add_f32_e32 v87, v87, v91
	ds_read_b128 v[90:93], v100 offset:17408
	s_waitcnt lgkmcnt(0)
	v_mul_f32_e32 v91, v43, v91
	v_fmac_f32_e32 v91, v42, v90
	v_fmac_f32_e32 v91, v44, v92
	v_fmac_f32_e32 v91, v45, v93
	v_add_f32_e32 v86, v86, v91
	ds_read_b128 v[90:93], v100 offset:21504
	s_waitcnt lgkmcnt(0)
	v_mul_f32_e32 v91, v43, v91
	v_fmac_f32_e32 v91, v42, v90
	v_fmac_f32_e32 v91, v44, v92
	v_fmac_f32_e32 v91, v45, v93
	v_add_f32_e32 v85, v85, v91
	ds_read_b128 v[90:93], v100 offset:25600
	s_waitcnt lgkmcnt(0)
	v_mul_f32_e32 v91, v43, v91
	v_fmac_f32_e32 v91, v42, v90
	v_fmac_f32_e32 v91, v44, v92
	v_fmac_f32_e32 v91, v45, v93
	v_add_f32_e32 v99, v49, v91
	ds_read_b128 v[90:93], v100 offset:29696
	s_waitcnt lgkmcnt(0)
	v_mul_f32_e32 v43, v43, v91
	v_fmac_f32_e32 v43, v42, v90
	v_fmac_f32_e32 v43, v44, v92
	v_fmac_f32_e32 v43, v45, v93
	v_add_f32_e32 v103, v48, v43
	ds_read_b128 v[42:45], v100 offset:38912
	ds_read_b128 v[90:93], v84 offset:2048
	ds_read_b128 v[94:97], v83 offset:2048
	s_waitcnt lgkmcnt(2)
	v_pk_mul_f32 v[38:39], v[38:39], v[42:43]
	s_waitcnt lgkmcnt(1)
	v_pk_add_f32 v[42:43], v[90:91], 1.0 op_sel_hi:[1,0]
	s_waitcnt lgkmcnt(0)
	v_pk_fma_f32 v[48:49], v[38:39], v[42:43], v[94:95]
	v_pk_mul_f32 v[38:39], v[40:41], v[76:77] op_sel_hi:[1,0]
	v_pk_add_f32 v[40:41], v[92:93], 1.0 op_sel_hi:[1,0]
	v_pk_mul_f32 v[38:39], v[38:39], v[44:45]
	s_nop 0
	v_pk_fma_f32 v[44:45], v[38:39], v[40:41], v[96:97]
	v_cvt_pk_bf16_f32 v38, v48, v49
	v_cvt_pk_bf16_f32 v39, v44, v45
	global_store_dwordx2 v[46:47], v[38:39], off offset:1024
	ds_read_b128 v[38:41], v100 offset:2048
	s_waitcnt lgkmcnt(0)
	v_mul_f32_e32 v39, v49, v39
	v_fmac_f32_e32 v39, v48, v38
	v_fmac_f32_e32 v39, v44, v40
	v_fmac_f32_e32 v39, v45, v41
	v_add_f32_e32 v43, v88, v39
	ds_read_b128 v[38:41], v100 offset:6144
	s_waitcnt lgkmcnt(0)
	v_mul_f32_e32 v39, v49, v39
	v_fmac_f32_e32 v39, v48, v38
	v_fmac_f32_e32 v39, v44, v40
	v_fmac_f32_e32 v39, v45, v41
	v_add_f32_e32 v104, v89, v39
	ds_read_b128 v[38:41], v100 offset:10240
	s_waitcnt lgkmcnt(0)
	v_mul_f32_e32 v39, v49, v39
	v_fmac_f32_e32 v39, v48, v38
	v_fmac_f32_e32 v39, v44, v40
	v_fmac_f32_e32 v39, v45, v41
	v_add_f32_e32 v98, v98, v39
	ds_read_b128 v[38:41], v100 offset:14336
	s_waitcnt lgkmcnt(0)
	v_mul_f32_e32 v39, v49, v39
	v_fmac_f32_e32 v39, v48, v38
	v_fmac_f32_e32 v39, v44, v40
	v_fmac_f32_e32 v39, v45, v41
	v_add_f32_e32 v42, v87, v39
	ds_read_b128 v[38:41], v100 offset:18432
	s_waitcnt lgkmcnt(0)
	v_mul_f32_e32 v39, v49, v39
	v_fmac_f32_e32 v39, v48, v38
	v_fmac_f32_e32 v39, v44, v40
	v_fmac_f32_e32 v39, v45, v41
	v_add_f32_e32 v41, v86, v39
	ds_read_b128 v[86:89], v100 offset:22528
	s_waitcnt lgkmcnt(0)
	v_mul_f32_e32 v38, v49, v87
	v_fmac_f32_e32 v38, v48, v86
	v_fmac_f32_e32 v38, v44, v88
	v_fmac_f32_e32 v38, v45, v89
	ds_read_b128 v[86:89], v100 offset:26624
	v_add_f32_e32 v40, v85, v38
	s_waitcnt lgkmcnt(0)
	v_mul_f32_e32 v38, v49, v87
	v_fmac_f32_e32 v38, v48, v86
	v_fmac_f32_e32 v38, v44, v88
	v_fmac_f32_e32 v38, v45, v89
	ds_read_b128 v[86:89], v100 offset:30720
	v_add_f32_e32 v39, v99, v38
	s_waitcnt lgkmcnt(0)
	v_mul_f32_e32 v38, v49, v87
	v_fmac_f32_e32 v38, v48, v86
	v_fmac_f32_e32 v38, v44, v88
	v_fmac_f32_e32 v38, v45, v89
	ds_read_b128 v[86:89], v100 offset:39936
	ds_read_b128 v[90:93], v84 offset:3072
	ds_read_b128 v[94:97], v83 offset:3072
	v_add_f32_e32 v38, v103, v38
	s_waitcnt lgkmcnt(2)
	v_pk_mul_f32 v[34:35], v[34:35], v[86:87]
	s_waitcnt lgkmcnt(1)
	v_pk_add_f32 v[44:45], v[90:91], 1.0 op_sel_hi:[1,0]
	v_pk_mul_f32 v[36:37], v[36:37], v[88:89]
	s_waitcnt lgkmcnt(0)
	v_pk_fma_f32 v[34:35], v[34:35], v[44:45], v[94:95]
	v_pk_add_f32 v[44:45], v[92:93], 1.0 op_sel_hi:[1,0]
	s_nop 0
	v_pk_fma_f32 v[36:37], v[36:37], v[44:45], v[96:97]
	v_cvt_pk_bf16_f32 v44, v34, v35
	v_cvt_pk_bf16_f32 v45, v36, v37
	global_store_dwordx2 v[46:47], v[44:45], off offset:1536
	ds_read_b128 v[44:47], v100 offset:3072
	s_waitcnt lgkmcnt(0)
	v_mul_f32_e32 v45, v35, v45
	v_fmac_f32_e32 v45, v34, v44
	v_fmac_f32_e32 v45, v36, v46
	v_fmac_f32_e32 v45, v37, v47
	v_add_f32_e32 v43, v43, v45
	ds_read_b128 v[44:47], v100 offset:7168
	s_waitcnt lgkmcnt(0)
	v_mul_f32_e32 v45, v35, v45
	v_fmac_f32_e32 v45, v34, v44
	v_fmac_f32_e32 v45, v36, v46
	v_fmac_f32_e32 v45, v37, v47
	v_add_f32_e32 v48, v104, v45
	ds_read_b128 v[44:47], v100 offset:11264
	s_waitcnt lgkmcnt(0)
	v_mul_f32_e32 v45, v35, v45
	v_fmac_f32_e32 v45, v34, v44
	v_fmac_f32_e32 v45, v36, v46
	v_fmac_f32_e32 v45, v37, v47
	v_add_f32_e32 v49, v98, v45
	ds_read_b128 v[44:47], v100 offset:15360
	s_waitcnt lgkmcnt(0)
	v_mul_f32_e32 v45, v35, v45
	v_fmac_f32_e32 v45, v34, v44
	v_fmac_f32_e32 v45, v36, v46
	v_fmac_f32_e32 v45, v37, v47
	v_add_f32_e32 v42, v42, v45
	ds_read_b128 v[44:47], v100 offset:19456
	s_waitcnt lgkmcnt(0)
	v_mul_f32_e32 v45, v35, v45
	v_fmac_f32_e32 v45, v34, v44
	v_fmac_f32_e32 v45, v36, v46
	v_fmac_f32_e32 v45, v37, v47
	v_add_f32_e32 v41, v41, v45
	ds_read_b128 v[44:47], v100 offset:23552
	s_waitcnt lgkmcnt(0)
	v_mul_f32_e32 v45, v35, v45
	v_fmac_f32_e32 v45, v34, v44
	v_fmac_f32_e32 v45, v36, v46
	v_fmac_f32_e32 v45, v37, v47
	v_add_f32_e32 v40, v40, v45
	ds_read_b128 v[44:47], v100 offset:27648
	s_waitcnt lgkmcnt(0)
	v_mul_f32_e32 v45, v35, v45
	v_fmac_f32_e32 v45, v34, v44
	v_fmac_f32_e32 v45, v36, v46
	v_fmac_f32_e32 v45, v37, v47
	v_add_f32_e32 v39, v39, v45
	ds_read_b128 v[44:47], v100 offset:31744
	s_waitcnt lgkmcnt(0)
	v_mul_f32_e32 v35, v35, v45
	v_fmac_f32_e32 v35, v34, v44
	v_fmac_f32_e32 v35, v36, v46
	v_cndmask_b32_e64 v36, v43, v41, s[40:41]
	v_fmac_f32_e32 v35, v37, v47
	ds_bpermute_b32 v36, v249, v36
	v_cndmask_b32_e64 v37, v48, v40, s[40:41]
	v_add_f32_e32 v34, v38, v35
	ds_bpermute_b32 v37, v249, v37
	v_cndmask_b32_e64 v38, v49, v39, s[40:41]
	ds_bpermute_b32 v38, v249, v38
	v_cndmask_b32_e64 v35, v41, v43, s[40:41]
	s_waitcnt lgkmcnt(2)
	v_add_f32_e32 v35, v35, v36
	v_cndmask_b32_e64 v36, v40, v48, s[40:41]
	s_waitcnt lgkmcnt(1)
	v_add_f32_e32 v36, v36, v37
	v_cndmask_b32_e64 v37, v39, v49, s[40:41]
	s_waitcnt lgkmcnt(0)
	v_add_f32_e32 v37, v37, v38
	v_cndmask_b32_e64 v38, v34, v42, s[40:41]
	v_cndmask_b32_e64 v34, v42, v34, s[40:41]
	ds_bpermute_b32 v34, v249, v34
	s_waitcnt lgkmcnt(0)
	v_add_f32_e32 v34, v38, v34
	v_cndmask_b32_e64 v38, v37, v35, s[42:43]
	v_cndmask_b32_e64 v35, v35, v37, s[42:43]
	v_cndmask_b32_e64 v37, v34, v36, s[42:43]
	v_cndmask_b32_e64 v34, v36, v34, s[42:43]
	ds_bpermute_b32 v35, v248, v35
	ds_bpermute_b32 v34, v248, v34
	s_waitcnt lgkmcnt(1)
	v_add_f32_e32 v35, v38, v35
	s_waitcnt lgkmcnt(0)
	v_add_f32_e32 v34, v37, v34
	v_cndmask_b32_e64 v36, v34, v35, s[44:45]
	v_cndmask_b32_e64 v34, v35, v34, s[44:45]
	ds_bpermute_b32 v34, v247, v34
	s_waitcnt lgkmcnt(0)
	v_add_f32_e32 v34, v36, v34
	ds_bpermute_b32 v35, v246, v34
	s_waitcnt lgkmcnt(0)
	v_add_f32_e32 v34, v34, v35
	ds_bpermute_b32 v35, v245, v34
	s_waitcnt lgkmcnt(0)
	v_add_f32_e32 v34, v34, v35
	ds_bpermute_b32 v35, v244, v34
	s_and_saveexec_b64 s[18:19], s[46:47]
	s_cbranch_execz .LBB0_450
	s_lshl_b64 s[2:3], s[52:53], 5
	s_waitcnt lgkmcnt(0)
	v_add_f32_e32 v36, v34, v35
	v_lshl_add_u64 v[34:35], v[64:65], 0, s[2:3]
	global_store_dword v[34:35], v36, off
	s_branch .LBB0_450
